# v58 + P4 EpiH rewritten by hand: x loads of 4 row blocks in flight with counted vmcnt (baseline waited vmcnt(0) 16 times per unit), saddr addressing, ss reduced with permlane swaps
# speedup vs baseline: 1.0083x; 1.0083x over previous
; #define PG8_STAGE(bufoff, gbase, voff) do { _Pragma("unroll") for (int _i = 0; _i < 2; ++_i) \
;         __builtin_amdgcn_global_load_lds((const unsigned*)((const char*)(gbase) + (voff)[_i]), (PG8_LAS unsigned*)(lds + (bufoff) + ldsw + _i * 8192), 16, 0, 0); } while (0)
; #define PG8_LDA(dst, b, h) do { _Pragma("unroll") for (int m = 0; m < 4; ++m) _Pragma("unroll") for (int k = 0; k < 2; ++k) dst[m][k] = *(const PG8_LAS bf16x8*)(lds + PG8_SA(b, h) + aoff + m * 2048 + k * 1024); } while (0)
; #define PG8_LDB(dst, b, h) do { _Pragma("unroll") for (int n = 0; n < 2; ++n) _Pragma("unroll") for (int k = 0; k < 2; ++k) dst[n][k] = *(const PG8_LAS bf16x8*)(lds + PG8_SB(b, h) + boff + n * 2048 + k * 1024); } while (0)
; #define PG8_MMA(ai, bj, At, Bt) do { __builtin_amdgcn_s_setprio(1); _Pragma("unroll") for (int m = 0; m < 4; ++m) _Pragma("unroll") for (int n = 0; n < 2; ++n) _Pragma("unroll") for (int k = 0; k < 2; ++k) \
;         acc[ai][bj][m][n] = __builtin_amdgcn_mfma_f32_16x16x32_bf16(Bt[n][k], At[m][k], acc[ai][bj][m][n], 0, 0, 0); __builtin_amdgcn_s_setprio(0); } while (0)
; #define PG8_WAIT_V(n) asm volatile("s_waitcnt vmcnt(" #n ")" ::: "memory")
; #define PG8_WAIT_L(n) asm volatile("s_waitcnt lgkmcnt(" #n ")" ::: "memory")
; #define PG8_BAR __builtin_amdgcn_s_barrier()
; #define PG8_SCHED __builtin_amdgcn_sched_barrier(0)
; template <class Epi, class Sched, bool ALIGN_EPI = false, bool SP2 = false>
; __device__ __forceinline__ void gemm_phase(PG8_LAS unsigned char* lds, const Gemm g, const Sched& S, const Epi& E) {
;     ...
;             PG8_WAIT_V(8); PG8_WAIT_L(0); PG8_BAR; PG8_MMA(1, 0, At, B0); PG8_MMA(1, 1, At, B1); PG8_BAR; PG8_SCHED;
;             PG8_LDB(B0, 1, 0); PG8_LDB(B1, 1, 1); PG8_SCHED; PG8_LDA(At, 1, 0); PG8_STAGE(PG8_SA(0, 1), a2 + hstep, voffA);
;             PG8_WAIT_V(8); PG8_WAIT_L(0); PG8_BAR; PG8_MMA(0, 0, At, B0); PG8_MMA(0, 1, At, B1); PG8_BAR; PG8_SCHED;
.Lrj_P4_1:
	s_waitcnt lgkmcnt(0)
	s_barrier
	s_setprio 1
	s_waitcnt lgkmcnt(0)
	v_mfma_f32_16x16x32_bf16 v[68:71], v[56:59], v[186:189], v[68:71]
	v_mfma_f32_16x16x32_bf16 v[64:67], v[72:75], v[186:189], v[64:67]
	v_mfma_f32_16x16x32_bf16 v[44:47], v[56:59], v[194:197], v[44:47]
	v_mfma_f32_16x16x32_bf16 v[40:43], v[72:75], v[194:197], v[40:43]
	v_mfma_f32_16x16x32_bf16 v[28:31], v[56:59], v[202:205], v[28:31]
	v_mfma_f32_16x16x32_bf16 v[24:27], v[72:75], v[202:205], v[24:27]
	v_mfma_f32_16x16x32_bf16 v[12:15], v[56:59], v[210:213], v[12:15]
	v_mfma_f32_16x16x32_bf16 v[8:11], v[72:75], v[210:213], v[8:11]
	v_mfma_f32_16x16x32_bf16 v[68:71], v[60:63], v[190:193], v[68:71]
	v_mfma_f32_16x16x32_bf16 v[64:67], v[76:79], v[190:193], v[64:67]
	v_mfma_f32_16x16x32_bf16 v[44:47], v[60:63], v[198:201], v[44:47]
	v_mfma_f32_16x16x32_bf16 v[40:43], v[76:79], v[198:201], v[40:43]
	v_mfma_f32_16x16x32_bf16 v[28:31], v[60:63], v[206:209], v[28:31]
	v_mfma_f32_16x16x32_bf16 v[24:27], v[76:79], v[206:209], v[24:27]
	v_mfma_f32_16x16x32_bf16 v[12:15], v[60:63], v[214:217], v[12:15]
	v_mfma_f32_16x16x32_bf16 v[8:11], v[76:79], v[214:217], v[8:11]
	s_setprio 0
	s_setprio 1
	v_mfma_f32_16x16x32_bf16 v[52:55], v[162:165], v[186:189], v[52:55]
	v_mfma_f32_16x16x32_bf16 v[48:51], v[178:181], v[186:189], v[48:51]
	v_mfma_f32_16x16x32_bf16 v[36:39], v[162:165], v[194:197], v[36:39]
	v_mfma_f32_16x16x32_bf16 v[32:35], v[178:181], v[194:197], v[32:35]
	v_mfma_f32_16x16x32_bf16 v[20:23], v[162:165], v[202:205], v[20:23]
	v_mfma_f32_16x16x32_bf16 v[16:19], v[178:181], v[202:205], v[16:19]
	v_mfma_f32_16x16x32_bf16 v[4:7], v[162:165], v[210:213], v[4:7]
	v_mfma_f32_16x16x32_bf16 v[0:3], v[178:181], v[210:213], v[0:3]
	v_mfma_f32_16x16x32_bf16 v[52:55], v[166:169], v[190:193], v[52:55]
	v_mfma_f32_16x16x32_bf16 v[48:51], v[182:185], v[190:193], v[48:51]
	v_mfma_f32_16x16x32_bf16 v[36:39], v[166:169], v[198:201], v[36:39]
	v_mfma_f32_16x16x32_bf16 v[32:35], v[182:185], v[198:201], v[32:35]
	v_mfma_f32_16x16x32_bf16 v[20:23], v[166:169], v[206:209], v[20:23]
	v_mfma_f32_16x16x32_bf16 v[16:19], v[182:185], v[206:209], v[16:19]
	v_mfma_f32_16x16x32_bf16 v[4:7], v[166:169], v[214:217], v[4:7]
	v_mfma_f32_16x16x32_bf16 v[0:3], v[182:185], v[214:217], v[0:3]
	s_setprio 0
	s_barrier
	s_add_i32 s76, 0, 0x18000
	s_add_i32 s77, 0, 0x1c000
	v_add_u32_e32 v76, s76, v171
	v_add_u32_e32 v152, s77, v171
	ds_read_b128 v[56:59], v76
	ds_read_b128 v[60:63], v76 offset:1024
	ds_read_b128 v[72:75], v76 offset:2048
	ds_read_b128 v[76:79], v76 offset:3072
	ds_read_b128 v[162:165], v152
	ds_read_b128 v[166:169], v152 offset:1024
	ds_read_b128 v[178:181], v152 offset:2048
	ds_read_b128 v[182:185], v152 offset:3072
	s_add_u32 s38, s38, 0x40000
	s_addc_u32 s39, s39, 0
	s_mov_b32 m0, s46
	v_lshl_add_u64 v[228:229], s[38:39], 0, v[144:145]
	ds_read_b128 v[186:189], v175 offset:32768
	ds_read_b128 v[190:193], v175 offset:33792
	ds_read_b128 v[194:197], v175 offset:34816
	ds_read_b128 v[198:201], v175 offset:35840
	ds_read_b128 v[202:205], v175 offset:36864
	ds_read_b128 v[206:209], v175 offset:37888
	ds_read_b128 v[210:213], v175 offset:38912
	ds_read_b128 v[214:217], v175 offset:39936
	global_load_lds_dwordx4 v[228:229], off
	v_lshl_add_u64 v[228:229], s[38:39], 0, v[148:149]
	s_mov_b32 m0, s47
	s_nop 0
	global_load_lds_dwordx4 v[228:229], off
	s_waitcnt vmcnt(8)
	s_waitcnt lgkmcnt(0)
	s_barrier
	s_setprio 1
	s_waitcnt lgkmcnt(0)
	v_mfma_f32_16x16x32_bf16 v[140:143], v[56:59], v[186:189], v[140:143]
	v_mfma_f32_16x16x32_bf16 v[136:139], v[72:75], v[186:189], v[136:139]
	v_mfma_f32_16x16x32_bf16 v[124:127], v[56:59], v[194:197], v[124:127]
	v_mfma_f32_16x16x32_bf16 v[120:123], v[72:75], v[194:197], v[120:123]
	v_mfma_f32_16x16x32_bf16 v[108:111], v[56:59], v[202:205], v[108:111]
	v_mfma_f32_16x16x32_bf16 v[104:107], v[72:75], v[202:205], v[104:107]
	v_mfma_f32_16x16x32_bf16 v[92:95], v[56:59], v[210:213], v[92:95]
	v_mfma_f32_16x16x32_bf16 v[88:91], v[72:75], v[210:213], v[88:91]
	v_mfma_f32_16x16x32_bf16 v[140:143], v[60:63], v[190:193], v[140:143]
	v_mfma_f32_16x16x32_bf16 v[136:139], v[76:79], v[190:193], v[136:139]
	v_mfma_f32_16x16x32_bf16 v[124:127], v[60:63], v[198:201], v[124:127]
	v_mfma_f32_16x16x32_bf16 v[120:123], v[76:79], v[198:201], v[120:123]
	v_mfma_f32_16x16x32_bf16 v[108:111], v[60:63], v[206:209], v[108:111]
	v_mfma_f32_16x16x32_bf16 v[104:107], v[76:79], v[206:209], v[104:107]
	v_mfma_f32_16x16x32_bf16 v[92:95], v[60:63], v[214:217], v[92:95]
	v_mfma_f32_16x16x32_bf16 v[88:91], v[76:79], v[214:217], v[88:91]
	s_setprio 0
	s_setprio 1
	v_mfma_f32_16x16x32_bf16 v[132:135], v[162:165], v[186:189], v[132:135]
	v_mfma_f32_16x16x32_bf16 v[128:131], v[178:181], v[186:189], v[128:131]
	v_mfma_f32_16x16x32_bf16 v[116:119], v[162:165], v[194:197], v[116:119]
	v_mfma_f32_16x16x32_bf16 v[112:115], v[178:181], v[194:197], v[112:115]
	v_mfma_f32_16x16x32_bf16 v[100:103], v[162:165], v[202:205], v[100:103]
	v_mfma_f32_16x16x32_bf16 v[96:99], v[178:181], v[202:205], v[96:99]
	v_mfma_f32_16x16x32_bf16 v[84:87], v[162:165], v[210:213], v[84:87]
	v_mfma_f32_16x16x32_bf16 v[80:83], v[178:181], v[210:213], v[80:83]
	v_mfma_f32_16x16x32_bf16 v[132:135], v[166:169], v[190:193], v[132:135]
	v_mfma_f32_16x16x32_bf16 v[128:131], v[182:185], v[190:193], v[128:131]
	v_mfma_f32_16x16x32_bf16 v[116:119], v[166:169], v[198:201], v[116:119]
	v_mfma_f32_16x16x32_bf16 v[112:115], v[182:185], v[198:201], v[112:115]
	v_mfma_f32_16x16x32_bf16 v[100:103], v[166:169], v[206:209], v[100:103]
	v_mfma_f32_16x16x32_bf16 v[96:99], v[182:185], v[206:209], v[96:99]
	v_mfma_f32_16x16x32_bf16 v[84:87], v[166:169], v[214:217], v[84:87]
	v_mfma_f32_16x16x32_bf16 v[80:83], v[182:185], v[214:217], v[80:83]
	s_setprio 0
	s_barrier
; #define PG8_STAGE(bufoff, gbase, voff) do { _Pragma("unroll") for (int _i = 0; _i < 2; ++_i) \
;         __builtin_amdgcn_global_load_lds((const unsigned*)((const char*)(gbase) + (voff)[_i]), (PG8_LAS unsigned*)(lds + (bufoff) + ldsw + _i * 8192), 16, 0, 0); } while (0)
; #define PG8_LDA(dst, b, h) do { _Pragma("unroll") for (int m = 0; m < 4; ++m) _Pragma("unroll") for (int k = 0; k < 2; ++k) dst[m][k] = *(const PG8_LAS bf16x8*)(lds + PG8_SA(b, h) + aoff + m * 2048 + k * 1024); } while (0)
; #define PG8_MMA(ai, bj, At, Bt) do { __builtin_amdgcn_s_setprio(1); _Pragma("unroll") for (int m = 0; m < 4; ++m) _Pragma("unroll") for (int n = 0; n < 2; ++n) _Pragma("unroll") for (int k = 0; k < 2; ++k) \
;         acc[ai][bj][m][n] = __builtin_amdgcn_mfma_f32_16x16x32_bf16(Bt[n][k], At[m][k], acc[ai][bj][m][n], 0, 0, 0); __builtin_amdgcn_s_setprio(0); } while (0)
; #define PG8_WAIT_V(n) asm volatile("s_waitcnt vmcnt(" #n ")" ::: "memory")
; #define PG8_WAIT_L(n) asm volatile("s_waitcnt lgkmcnt(" #n ")" ::: "memory")
; template <class Epi, class Sched, bool ALIGN_EPI = false, bool SP2 = false>
; __device__ __forceinline__ void gemm_phase(PG8_LAS unsigned char* lds, const Gemm g, const Sched& S, const Epi& E) {
;     ...
;             PG8_LDA(At, 1, 1); PG8_STAGE(PG8_SB(1, 0), b3, voffB); PG8_STAGE(PG8_SB(1, 1), b3 + hstep, voffB); PG8_STAGE(PG8_SA(1, 0), a3, voffA);
;             PG8_WAIT_V(8); PG8_WAIT_L(0); PG8_BAR; PG8_MMA(1, 0, At, B0); PG8_MMA(1, 1, At, B1); PG8_BAR; PG8_SCHED;
;     __device__ __forceinline__ void operator()(const f32x4 (&acc)[2][2][4][2], const Unit& u, int wr, int wc, int fr, int fq) const {
;         const int rbase = u.pm * 256 + wr * 64 + fr, cb = u.pn * 256 + wc * 32 + fq * 8;
;         f32x4 w[2][2];
; #pragma unroll
;         for (int bj = 0; bj < 2; ++bj) { w[bj][0] = *(const f32x4*)(ln2 + cb + bj * 128); w[bj][1] = *(const f32x4*)(ln2 + cb + bj * 128 + 4); }
; #pragma unroll
;         for (int ai = 0; ai < 2; ++ai)
; #pragma unroll
;             for (int m = 0; m < 4; ++m) { const int row = rbase + ai * 128 + m * 16; const float* xr = (row < MP ? xp + (size_t)row * 1024 : xs + (size_t)(row - MP) * 1024) + cb;
;                 float ss = 0.f;
; #pragma unroll
;                 for (int bj = 0; bj < 2; ++bj) { const f32x4 h0 = *(const f32x4*)(xr + bj * 128) + acc[ai][bj][m][0], h1 = *(const f32x4*)(xr + bj * 128 + 4) + acc[ai][bj][m][1];
	s_add_i32 s38, s76, s41
	v_lshl_add_u64 v[218:219], v[218:219], 0, s[18:19]
	s_mov_b32 m0, s38
	ds_read_b128 v[186:189], v175 offset:49152
	ds_read_b128 v[190:193], v175 offset:50176
	ds_read_b128 v[194:197], v175 offset:51200
	ds_read_b128 v[198:201], v175 offset:52224
	ds_read_b128 v[202:205], v175 offset:53248
	ds_read_b128 v[206:209], v175 offset:54272
	ds_read_b128 v[210:213], v175 offset:55296
	ds_read_b128 v[214:217], v175 offset:56320
	global_load_lds_dwordx4 v[218:219], off
	s_add_i32 m0, s38, 0x2000
	s_add_u32 s36, s36, 0x40080
	v_lshl_add_u64 v[218:219], v[220:221], 0, s[18:19]
	s_addc_u32 s37, s37, 0
	s_add_i32 s38, s77, s41
	global_load_lds_dwordx4 v[218:219], off
	v_lshl_add_u64 v[218:219], s[36:37], 0, v[146:147]
	s_mov_b32 m0, s38
	s_nop 0
	global_load_lds_dwordx4 v[218:219], off
	v_lshl_add_u64 v[218:219], s[36:37], 0, v[150:151]
	s_add_i32 m0, s38, 0x2000
	s_nop 0
	global_load_lds_dwordx4 v[218:219], off
	v_lshl_add_u64 v[218:219], v[222:223], 0, s[18:19]
	s_mov_b32 m0, s53
	s_nop 0
	global_load_lds_dwordx4 v[218:219], off
	v_lshl_add_u64 v[218:219], v[224:225], 0, s[18:19]
	s_mov_b32 m0, s60
	s_nop 0
	global_load_lds_dwordx4 v[218:219], off
	s_waitcnt vmcnt(8)
	s_waitcnt lgkmcnt(0)
	s_barrier
	s_setprio 1
	s_waitcnt lgkmcnt(0)
	v_mfma_f32_16x16x32_bf16 v[68:71], v[56:59], v[186:189], v[68:71]
	v_mfma_f32_16x16x32_bf16 v[64:67], v[72:75], v[186:189], v[64:67]
	v_mfma_f32_16x16x32_bf16 v[44:47], v[56:59], v[194:197], v[44:47]
	v_mfma_f32_16x16x32_bf16 v[40:43], v[72:75], v[194:197], v[40:43]
	v_mfma_f32_16x16x32_bf16 v[28:31], v[56:59], v[202:205], v[28:31]
	v_mfma_f32_16x16x32_bf16 v[24:27], v[72:75], v[202:205], v[24:27]
	v_mfma_f32_16x16x32_bf16 v[12:15], v[56:59], v[210:213], v[12:15]
	v_mfma_f32_16x16x32_bf16 v[8:11], v[72:75], v[210:213], v[8:11]
	v_mfma_f32_16x16x32_bf16 v[68:71], v[60:63], v[190:193], v[68:71]
	v_mfma_f32_16x16x32_bf16 v[64:67], v[76:79], v[190:193], v[64:67]
	v_mfma_f32_16x16x32_bf16 v[44:47], v[60:63], v[198:201], v[44:47]
	v_mfma_f32_16x16x32_bf16 v[40:43], v[76:79], v[198:201], v[40:43]
	v_mfma_f32_16x16x32_bf16 v[28:31], v[60:63], v[206:209], v[28:31]
	v_mfma_f32_16x16x32_bf16 v[24:27], v[76:79], v[206:209], v[24:27]
	v_mfma_f32_16x16x32_bf16 v[12:15], v[60:63], v[214:217], v[12:15]
	v_mfma_f32_16x16x32_bf16 v[8:11], v[76:79], v[214:217], v[8:11]
	s_setprio 0
	s_setprio 1
	v_mfma_f32_16x16x32_bf16 v[52:55], v[162:165], v[186:189], v[52:55]
	v_mfma_f32_16x16x32_bf16 v[48:51], v[178:181], v[186:189], v[48:51]
	v_mfma_f32_16x16x32_bf16 v[36:39], v[162:165], v[194:197], v[36:39]
	v_mfma_f32_16x16x32_bf16 v[32:35], v[178:181], v[194:197], v[32:35]
	v_mfma_f32_16x16x32_bf16 v[20:23], v[162:165], v[202:205], v[20:23]
	v_mfma_f32_16x16x32_bf16 v[16:19], v[178:181], v[202:205], v[16:19]
	v_mfma_f32_16x16x32_bf16 v[4:7], v[162:165], v[210:213], v[4:7]
	v_mfma_f32_16x16x32_bf16 v[0:3], v[178:181], v[210:213], v[0:3]
	v_mfma_f32_16x16x32_bf16 v[52:55], v[166:169], v[190:193], v[52:55]
	v_mfma_f32_16x16x32_bf16 v[48:51], v[182:185], v[190:193], v[48:51]
	v_mfma_f32_16x16x32_bf16 v[36:39], v[166:169], v[198:201], v[36:39]
	v_mfma_f32_16x16x32_bf16 v[32:35], v[182:185], v[198:201], v[32:35]
	v_mfma_f32_16x16x32_bf16 v[20:23], v[166:169], v[206:209], v[20:23]
	v_mfma_f32_16x16x32_bf16 v[16:19], v[182:185], v[206:209], v[16:19]
	v_mfma_f32_16x16x32_bf16 v[4:7], v[166:169], v[214:217], v[4:7]
	v_mfma_f32_16x16x32_bf16 v[0:3], v[182:185], v[214:217], v[0:3]
	s_setprio 0
	s_barrier
	s_mov_b32 s99, 0
	s_add_i32 s75, s75, 2
	s_add_u32 s34, s34, 0x100
	s_addc_u32 s35, s35, 0
	s_add_u32 s73, s73, 0x100
	s_addc_u32 s74, s74, 0
	s_cmp_gt_u32 s75, 13
	s_cbranch_scc0 .LBB0_1423
	v_lshl_or_b32 v162, s14, 8, v172
	v_lshl_add_u32 v163, s30, 8, v170
	v_lshlrev_b32_e32 v164, 12, v163
	v_lshl_add_u32 v164, v162, 2, v164
	v_lshlrev_b32_e32 v165, 11, v163
	v_lshl_add_u32 v165, v162, 1, v165
	s_lshl_b32 s31, s14, 4
	s_lshl_b32 s32, s52, 2
	s_add_i32 s31, s31, s32
	v_lshl_add_u32 v166, v163, 6, s31
	s_cmp_lt_u32 s30, 0x100
	s_cselect_b32 s36, s48, s50
	s_cselect_b32 s37, s49, s51
	s_cselect_b32 s38, 0, 0x10000000
	s_sub_u32 s36, s36, s38
	s_subb_u32 s37, s37, 0
	v_lshlrev_b32_e32 v167, 2, v162
	global_load_dwordx4 v[76:79], v167, s[78:79]
	global_load_dwordx4 v[72:75], v167, s[78:79] offset:16
	global_load_dwordx4 v[60:63], v167, s[78:79] offset:512
	global_load_dwordx4 v[56:59], v167, s[78:79] offset:528
	v_mov_b32_e32 v168, v164
	global_load_dwordx4 v[178:181], v168, s[36:37]
	global_load_dwordx4 v[182:185], v168, s[36:37] offset:16
	global_load_dwordx4 v[186:189], v168, s[36:37] offset:512
	global_load_dwordx4 v[190:193], v168, s[36:37] offset:528
	v_add_u32_e32 v168, 0x10000, v164
	global_load_dwordx4 v[194:197], v168, s[36:37]
	global_load_dwordx4 v[198:201], v168, s[36:37] offset:16
	global_load_dwordx4 v[202:205], v168, s[36:37] offset:512
	global_load_dwordx4 v[206:209], v168, s[36:37] offset:528
	v_add_u32_e32 v168, 0x20000, v164
	global_load_dwordx4 v[210:213], v168, s[36:37]
	global_load_dwordx4 v[214:217], v168, s[36:37] offset:16
	global_load_dwordx4 v[218:221], v168, s[36:37] offset:512
	global_load_dwordx4 v[222:225], v168, s[36:37] offset:528
	v_add_u32_e32 v168, 0x30000, v164
	global_load_dwordx4 v[228:231], v168, s[36:37]
	global_load_dwordx4 v[232:235], v168, s[36:37] offset:16
	global_load_dwordx4 v[236:239], v168, s[36:37] offset:512
	global_load_dwordx4 v[240:243], v168, s[36:37] offset:528
	s_and_b64 vcc, exec, s[20:21]
	s_cbranch_vccz .LBB0_1426
	s_barrier
; __device__ __forceinline__ u32x4 pack8(const f32x4 a, const f32x4 b) { u32x4 w; w.x = cvt_pk_bf16(a[0], a[1]); w.y = cvt_pk_bf16(a[2], a[3]); w.z = cvt_pk_bf16(b[0], b[1]); w.w = cvt_pk_bf16(b[2], b[3]); return w; }
; __device__ __forceinline__ float dot4(const f32x4 a, const f32x4 b) { return (a[0] * b[0] + a[1] * b[1]) + (a[2] * b[2] + a[3] * b[3]); }
;     __device__ __forceinline__ void operator()(const f32x4 (&acc)[2][2][4][2], const Unit& u, int wr, int wc, int fr, int fq) const {
;     ...
;             for (int m = 0; m < 4; ++m) { const int row = rbase + ai * 128 + m * 16; const float* xr = (row < MP ? xp + (size_t)row * 1024 : xs + (size_t)(row - MP) * 1024) + cb;
;                 float ss = 0.f;
; #pragma unroll
;                 for (int bj = 0; bj < 2; ++bj) { const f32x4 h0 = *(const f32x4*)(xr + bj * 128) + acc[ai][bj][m][0], h1 = *(const f32x4*)(xr + bj * 128 + 4) + acc[ai][bj][m][1];
;                     float* yp = y + (size_t)row * 1024 + cb + bj * 128; *(f32x4*)yp = h0; *(f32x4*)(yp + 4) = h1;
;                     ss += dot4(h0, h0) + dot4(h1, h1);
;                     *(u32x4*)(HN + (size_t)row * 1024 + cb + bj * 128) = pack8(h0 * w[bj][0], h1 * w[bj][1]); }
;                 ss += __shfl_xor(ss, 16); ss += __shfl_xor(ss, 32);
;                 if (fq == 0) SSP[(size_t)row * 16 + u.pn * 4 + wc] = ss;
;                 asm volatile("" ::: "memory"); }
.LBB0_1426:
	s_waitcnt vmcnt(12)
	v_pk_add_f32 v[140:141], v[140:141], v[178:179]
	v_pk_add_f32 v[142:143], v[142:143], v[180:181]
	v_pk_add_f32 v[136:137], v[136:137], v[182:183]
	v_pk_add_f32 v[138:139], v[138:139], v[184:185]
	v_pk_add_f32 v[132:133], v[132:133], v[186:187]
	v_pk_add_f32 v[134:135], v[134:135], v[188:189]
	v_pk_add_f32 v[128:129], v[128:129], v[190:191]
	v_pk_add_f32 v[130:131], v[130:131], v[192:193]
	v_mov_b32_e32 v168, v164
	global_store_dwordx4 v168, v[140:143], s[84:85]
	global_store_dwordx4 v168, v[136:139], s[84:85] offset:16
	global_store_dwordx4 v168, v[132:135], s[84:85] offset:512
	global_store_dwordx4 v168, v[128:131], s[84:85] offset:528
	v_pk_mul_f32 v[178:179], v[140:141], v[140:141]
	v_pk_mul_f32 v[180:181], v[132:133], v[132:133]
	v_pk_fma_f32 v[178:179], v[142:143], v[142:143], v[178:179]
	v_pk_fma_f32 v[180:181], v[134:135], v[134:135], v[180:181]
	v_pk_fma_f32 v[178:179], v[136:137], v[136:137], v[178:179]
	v_pk_fma_f32 v[180:181], v[128:129], v[128:129], v[180:181]
	v_pk_fma_f32 v[178:179], v[138:139], v[138:139], v[178:179]
	v_pk_fma_f32 v[180:181], v[130:131], v[130:131], v[180:181]
	v_pk_add_f32 v[178:179], v[178:179], v[180:181]
	v_add_f32_e32 v169, v178, v179
	v_mov_b32_e32 v177, v169
	v_pk_mul_f32 v[178:179], v[140:141], v[76:77]
	v_pk_mul_f32 v[180:181], v[142:143], v[78:79]
	v_pk_mul_f32 v[182:183], v[136:137], v[72:73]
	v_pk_mul_f32 v[184:185], v[138:139], v[74:75]
	v_pk_mul_f32 v[186:187], v[132:133], v[60:61]
	v_pk_mul_f32 v[188:189], v[134:135], v[62:63]
	v_pk_mul_f32 v[190:191], v[128:129], v[56:57]
	v_pk_mul_f32 v[192:193], v[130:131], v[58:59]
	v_permlane16_swap_b32_e32 v177, v169
	v_cvt_pk_bf16_f32 v178, v178, v179
	v_cvt_pk_bf16_f32 v179, v180, v181
	v_cvt_pk_bf16_f32 v180, v182, v183
	v_cvt_pk_bf16_f32 v181, v184, v185
	v_cvt_pk_bf16_f32 v182, v186, v187
	v_cvt_pk_bf16_f32 v183, v188, v189
	v_cvt_pk_bf16_f32 v184, v190, v191
	v_cvt_pk_bf16_f32 v185, v192, v193
	v_add_f32_e32 v169, v169, v177
	v_mov_b32_e32 v177, v169
	v_mov_b32_e32 v167, v165
	global_store_dwordx4 v167, v[178:181], s[10:11]
	global_store_dwordx4 v167, v[182:185], s[10:11] offset:256
	v_permlane32_swap_b32_e32 v177, v169
	v_mov_b32_e32 v152, v166
	s_nop 0
	v_add_f32_e32 v169, v169, v177
	s_and_saveexec_b64 s[34:35], s[4:5]
	global_store_dword v152, v169, s[12:13]
	s_mov_b64 exec, s[34:35]
	v_add_u32_e32 v168, 0x80000, v164
	global_load_dwordx4 v[178:181], v168, s[36:37]
	global_load_dwordx4 v[182:185], v168, s[36:37] offset:16
	global_load_dwordx4 v[186:189], v168, s[36:37] offset:512
	global_load_dwordx4 v[190:193], v168, s[36:37] offset:528
	s_waitcnt vmcnt(19)
	v_pk_add_f32 v[124:125], v[124:125], v[194:195]
	v_pk_add_f32 v[126:127], v[126:127], v[196:197]
	v_pk_add_f32 v[120:121], v[120:121], v[198:199]
	v_pk_add_f32 v[122:123], v[122:123], v[200:201]
	v_pk_add_f32 v[116:117], v[116:117], v[202:203]
	v_pk_add_f32 v[118:119], v[118:119], v[204:205]
	v_pk_add_f32 v[112:113], v[112:113], v[206:207]
	v_pk_add_f32 v[114:115], v[114:115], v[208:209]
	v_add_u32_e32 v168, 0x10000, v164
	global_store_dwordx4 v168, v[124:127], s[84:85]
	global_store_dwordx4 v168, v[120:123], s[84:85] offset:16
	global_store_dwordx4 v168, v[116:119], s[84:85] offset:512
	global_store_dwordx4 v168, v[112:115], s[84:85] offset:528
	v_pk_mul_f32 v[194:195], v[124:125], v[124:125]
	v_pk_mul_f32 v[196:197], v[116:117], v[116:117]
	v_pk_fma_f32 v[194:195], v[126:127], v[126:127], v[194:195]
	v_pk_fma_f32 v[196:197], v[118:119], v[118:119], v[196:197]
	v_pk_fma_f32 v[194:195], v[120:121], v[120:121], v[194:195]
	v_pk_fma_f32 v[196:197], v[112:113], v[112:113], v[196:197]
	v_pk_fma_f32 v[194:195], v[122:123], v[122:123], v[194:195]
	v_pk_fma_f32 v[196:197], v[114:115], v[114:115], v[196:197]
	v_pk_add_f32 v[194:195], v[194:195], v[196:197]
	v_add_f32_e32 v169, v194, v195
	v_mov_b32_e32 v177, v169
	v_pk_mul_f32 v[194:195], v[124:125], v[76:77]
	v_pk_mul_f32 v[196:197], v[126:127], v[78:79]
	v_pk_mul_f32 v[198:199], v[120:121], v[72:73]
	v_pk_mul_f32 v[200:201], v[122:123], v[74:75]
	v_pk_mul_f32 v[202:203], v[116:117], v[60:61]
	v_pk_mul_f32 v[204:205], v[118:119], v[62:63]
	v_pk_mul_f32 v[206:207], v[112:113], v[56:57]
	v_pk_mul_f32 v[208:209], v[114:115], v[58:59]
	v_permlane16_swap_b32_e32 v177, v169
	v_cvt_pk_bf16_f32 v194, v194, v195
	v_cvt_pk_bf16_f32 v195, v196, v197
	v_cvt_pk_bf16_f32 v196, v198, v199
	v_cvt_pk_bf16_f32 v197, v200, v201
	v_cvt_pk_bf16_f32 v198, v202, v203
	v_cvt_pk_bf16_f32 v199, v204, v205
	v_cvt_pk_bf16_f32 v200, v206, v207
	v_cvt_pk_bf16_f32 v201, v208, v209
	v_add_f32_e32 v169, v169, v177
	v_mov_b32_e32 v177, v169
	v_add_u32_e32 v167, 0x8000, v165
	global_store_dwordx4 v167, v[194:197], s[10:11]
	global_store_dwordx4 v167, v[198:201], s[10:11] offset:256
	v_permlane32_swap_b32_e32 v177, v169
	v_add_u32_e32 v152, 0x400, v166
	s_nop 0
	v_add_f32_e32 v169, v169, v177
	s_and_saveexec_b64 s[34:35], s[4:5]
	global_store_dword v152, v169, s[12:13]
	s_mov_b64 exec, s[34:35]
	v_add_u32_e32 v168, 0x90000, v164
	global_load_dwordx4 v[194:197], v168, s[36:37]
	global_load_dwordx4 v[198:201], v168, s[36:37] offset:16
	global_load_dwordx4 v[202:205], v168, s[36:37] offset:512
	global_load_dwordx4 v[206:209], v168, s[36:37] offset:528
	s_waitcnt vmcnt(26)
; __device__ __forceinline__ u32x4 pack8(const f32x4 a, const f32x4 b) { u32x4 w; w.x = cvt_pk_bf16(a[0], a[1]); w.y = cvt_pk_bf16(a[2], a[3]); w.z = cvt_pk_bf16(b[0], b[1]); w.w = cvt_pk_bf16(b[2], b[3]); return w; }
; __device__ __forceinline__ float dot4(const f32x4 a, const f32x4 b) { return (a[0] * b[0] + a[1] * b[1]) + (a[2] * b[2] + a[3] * b[3]); }
;     __device__ __forceinline__ void operator()(const f32x4 (&acc)[2][2][4][2], const Unit& u, int wr, int wc, int fr, int fq) const {
;     ...
;             for (int m = 0; m < 4; ++m) { const int row = rbase + ai * 128 + m * 16; const float* xr = (row < MP ? xp + (size_t)row * 1024 : xs + (size_t)(row - MP) * 1024) + cb;
;                 float ss = 0.f;
; #pragma unroll
;                 for (int bj = 0; bj < 2; ++bj) { const f32x4 h0 = *(const f32x4*)(xr + bj * 128) + acc[ai][bj][m][0], h1 = *(const f32x4*)(xr + bj * 128 + 4) + acc[ai][bj][m][1];
;                     float* yp = y + (size_t)row * 1024 + cb + bj * 128; *(f32x4*)yp = h0; *(f32x4*)(yp + 4) = h1;
;                     ss += dot4(h0, h0) + dot4(h1, h1);
;                     *(u32x4*)(HN + (size_t)row * 1024 + cb + bj * 128) = pack8(h0 * w[bj][0], h1 * w[bj][1]); }
;                 ss += __shfl_xor(ss, 16); ss += __shfl_xor(ss, 32);
;                 if (fq == 0) SSP[(size_t)row * 16 + u.pn * 4 + wc] = ss;
;                 asm volatile("" ::: "memory"); }
	v_pk_add_f32 v[108:109], v[108:109], v[210:211]
	v_pk_add_f32 v[110:111], v[110:111], v[212:213]
	v_pk_add_f32 v[104:105], v[104:105], v[214:215]
	v_pk_add_f32 v[106:107], v[106:107], v[216:217]
	v_pk_add_f32 v[100:101], v[100:101], v[218:219]
	v_pk_add_f32 v[102:103], v[102:103], v[220:221]
	v_pk_add_f32 v[96:97], v[96:97], v[222:223]
	v_pk_add_f32 v[98:99], v[98:99], v[224:225]
	v_add_u32_e32 v168, 0x20000, v164
	global_store_dwordx4 v168, v[108:111], s[84:85]
	global_store_dwordx4 v168, v[104:107], s[84:85] offset:16
	global_store_dwordx4 v168, v[100:103], s[84:85] offset:512
	global_store_dwordx4 v168, v[96:99], s[84:85] offset:528
	v_pk_mul_f32 v[210:211], v[108:109], v[108:109]
	v_pk_mul_f32 v[212:213], v[100:101], v[100:101]
	v_pk_fma_f32 v[210:211], v[110:111], v[110:111], v[210:211]
	v_pk_fma_f32 v[212:213], v[102:103], v[102:103], v[212:213]
	v_pk_fma_f32 v[210:211], v[104:105], v[104:105], v[210:211]
	v_pk_fma_f32 v[212:213], v[96:97], v[96:97], v[212:213]
	v_pk_fma_f32 v[210:211], v[106:107], v[106:107], v[210:211]
	v_pk_fma_f32 v[212:213], v[98:99], v[98:99], v[212:213]
	v_pk_add_f32 v[210:211], v[210:211], v[212:213]
	v_add_f32_e32 v169, v210, v211
	v_mov_b32_e32 v177, v169
	v_pk_mul_f32 v[210:211], v[108:109], v[76:77]
	v_pk_mul_f32 v[212:213], v[110:111], v[78:79]
	v_pk_mul_f32 v[214:215], v[104:105], v[72:73]
	v_pk_mul_f32 v[216:217], v[106:107], v[74:75]
	v_pk_mul_f32 v[218:219], v[100:101], v[60:61]
	v_pk_mul_f32 v[220:221], v[102:103], v[62:63]
	v_pk_mul_f32 v[222:223], v[96:97], v[56:57]
	v_pk_mul_f32 v[224:225], v[98:99], v[58:59]
	v_permlane16_swap_b32_e32 v177, v169
	v_cvt_pk_bf16_f32 v210, v210, v211
	v_cvt_pk_bf16_f32 v211, v212, v213
	v_cvt_pk_bf16_f32 v212, v214, v215
	v_cvt_pk_bf16_f32 v213, v216, v217
	v_cvt_pk_bf16_f32 v214, v218, v219
	v_cvt_pk_bf16_f32 v215, v220, v221
	v_cvt_pk_bf16_f32 v216, v222, v223
	v_cvt_pk_bf16_f32 v217, v224, v225
	v_add_f32_e32 v169, v169, v177
	v_mov_b32_e32 v177, v169
	v_add_u32_e32 v167, 0x10000, v165
	global_store_dwordx4 v167, v[210:213], s[10:11]
	global_store_dwordx4 v167, v[214:217], s[10:11] offset:256
	v_permlane32_swap_b32_e32 v177, v169
	v_add_u32_e32 v152, 0x800, v166
	s_nop 0
	v_add_f32_e32 v169, v169, v177
	s_and_saveexec_b64 s[34:35], s[4:5]
	global_store_dword v152, v169, s[12:13]
	s_mov_b64 exec, s[34:35]
	v_add_u32_e32 v168, 0xa0000, v164
	global_load_dwordx4 v[210:213], v168, s[36:37]
	global_load_dwordx4 v[214:217], v168, s[36:37] offset:16
	global_load_dwordx4 v[218:221], v168, s[36:37] offset:512
	global_load_dwordx4 v[222:225], v168, s[36:37] offset:528
	s_waitcnt vmcnt(33)
	v_pk_add_f32 v[92:93], v[92:93], v[228:229]
	v_pk_add_f32 v[94:95], v[94:95], v[230:231]
	v_pk_add_f32 v[88:89], v[88:89], v[232:233]
	v_pk_add_f32 v[90:91], v[90:91], v[234:235]
	v_pk_add_f32 v[84:85], v[84:85], v[236:237]
	v_pk_add_f32 v[86:87], v[86:87], v[238:239]
	v_pk_add_f32 v[80:81], v[80:81], v[240:241]
	v_pk_add_f32 v[82:83], v[82:83], v[242:243]
	v_add_u32_e32 v168, 0x30000, v164
	global_store_dwordx4 v168, v[92:95], s[84:85]
	global_store_dwordx4 v168, v[88:91], s[84:85] offset:16
	global_store_dwordx4 v168, v[84:87], s[84:85] offset:512
	global_store_dwordx4 v168, v[80:83], s[84:85] offset:528
	v_pk_mul_f32 v[228:229], v[92:93], v[92:93]
	v_pk_mul_f32 v[230:231], v[84:85], v[84:85]
	v_pk_fma_f32 v[228:229], v[94:95], v[94:95], v[228:229]
	v_pk_fma_f32 v[230:231], v[86:87], v[86:87], v[230:231]
	v_pk_fma_f32 v[228:229], v[88:89], v[88:89], v[228:229]
	v_pk_fma_f32 v[230:231], v[80:81], v[80:81], v[230:231]
	v_pk_fma_f32 v[228:229], v[90:91], v[90:91], v[228:229]
	v_pk_fma_f32 v[230:231], v[82:83], v[82:83], v[230:231]
	v_pk_add_f32 v[228:229], v[228:229], v[230:231]
	v_add_f32_e32 v169, v228, v229
	v_mov_b32_e32 v177, v169
	v_pk_mul_f32 v[228:229], v[92:93], v[76:77]
	v_pk_mul_f32 v[230:231], v[94:95], v[78:79]
	v_pk_mul_f32 v[232:233], v[88:89], v[72:73]
	v_pk_mul_f32 v[234:235], v[90:91], v[74:75]
	v_pk_mul_f32 v[236:237], v[84:85], v[60:61]
	v_pk_mul_f32 v[238:239], v[86:87], v[62:63]
	v_pk_mul_f32 v[240:241], v[80:81], v[56:57]
	v_pk_mul_f32 v[242:243], v[82:83], v[58:59]
	v_permlane16_swap_b32_e32 v177, v169
	v_cvt_pk_bf16_f32 v228, v228, v229
	v_cvt_pk_bf16_f32 v229, v230, v231
	v_cvt_pk_bf16_f32 v230, v232, v233
	v_cvt_pk_bf16_f32 v231, v234, v235
	v_cvt_pk_bf16_f32 v232, v236, v237
	v_cvt_pk_bf16_f32 v233, v238, v239
	v_cvt_pk_bf16_f32 v234, v240, v241
	v_cvt_pk_bf16_f32 v235, v242, v243
	v_add_f32_e32 v169, v169, v177
	v_mov_b32_e32 v177, v169
	v_add_u32_e32 v167, 0x18000, v165
	global_store_dwordx4 v167, v[228:231], s[10:11]
	global_store_dwordx4 v167, v[232:235], s[10:11] offset:256
	v_permlane32_swap_b32_e32 v177, v169
	v_add_u32_e32 v152, 0xc00, v166
	s_nop 0
	v_add_f32_e32 v169, v169, v177
	s_and_saveexec_b64 s[34:35], s[4:5]
	global_store_dword v152, v169, s[12:13]
	s_mov_b64 exec, s[34:35]
	v_add_u32_e32 v168, 0xb0000, v164
	global_load_dwordx4 v[228:231], v168, s[36:37]
	global_load_dwordx4 v[232:235], v168, s[36:37] offset:16
	global_load_dwordx4 v[236:239], v168, s[36:37] offset:512
	global_load_dwordx4 v[240:243], v168, s[36:37] offset:528
	s_waitcnt vmcnt(33)
; __device__ __forceinline__ u32x4 pack8(const f32x4 a, const f32x4 b) { u32x4 w; w.x = cvt_pk_bf16(a[0], a[1]); w.y = cvt_pk_bf16(a[2], a[3]); w.z = cvt_pk_bf16(b[0], b[1]); w.w = cvt_pk_bf16(b[2], b[3]); return w; }
; __device__ __forceinline__ float dot4(const f32x4 a, const f32x4 b) { return (a[0] * b[0] + a[1] * b[1]) + (a[2] * b[2] + a[3] * b[3]); }
;     __device__ __forceinline__ void operator()(const f32x4 (&acc)[2][2][4][2], const Unit& u, int wr, int wc, int fr, int fq) const {
;     ...
;             for (int m = 0; m < 4; ++m) { const int row = rbase + ai * 128 + m * 16; const float* xr = (row < MP ? xp + (size_t)row * 1024 : xs + (size_t)(row - MP) * 1024) + cb;
;                 float ss = 0.f;
; #pragma unroll
;                 for (int bj = 0; bj < 2; ++bj) { const f32x4 h0 = *(const f32x4*)(xr + bj * 128) + acc[ai][bj][m][0], h1 = *(const f32x4*)(xr + bj * 128 + 4) + acc[ai][bj][m][1];
;                     float* yp = y + (size_t)row * 1024 + cb + bj * 128; *(f32x4*)yp = h0; *(f32x4*)(yp + 4) = h1;
;                     ss += dot4(h0, h0) + dot4(h1, h1);
;                     *(u32x4*)(HN + (size_t)row * 1024 + cb + bj * 128) = pack8(h0 * w[bj][0], h1 * w[bj][1]); }
;                 ss += __shfl_xor(ss, 16); ss += __shfl_xor(ss, 32);
;                 if (fq == 0) SSP[(size_t)row * 16 + u.pn * 4 + wc] = ss;
;                 asm volatile("" ::: "memory"); }
	v_pk_add_f32 v[68:69], v[68:69], v[178:179]
	v_pk_add_f32 v[70:71], v[70:71], v[180:181]
	v_pk_add_f32 v[64:65], v[64:65], v[182:183]
	v_pk_add_f32 v[66:67], v[66:67], v[184:185]
	v_pk_add_f32 v[52:53], v[52:53], v[186:187]
	v_pk_add_f32 v[54:55], v[54:55], v[188:189]
	v_pk_add_f32 v[48:49], v[48:49], v[190:191]
	v_pk_add_f32 v[50:51], v[50:51], v[192:193]
	v_add_u32_e32 v168, 0x80000, v164
	global_store_dwordx4 v168, v[68:71], s[84:85]
	global_store_dwordx4 v168, v[64:67], s[84:85] offset:16
	global_store_dwordx4 v168, v[52:55], s[84:85] offset:512
	global_store_dwordx4 v168, v[48:51], s[84:85] offset:528
	v_pk_mul_f32 v[178:179], v[68:69], v[68:69]
	v_pk_mul_f32 v[180:181], v[52:53], v[52:53]
	v_pk_fma_f32 v[178:179], v[70:71], v[70:71], v[178:179]
	v_pk_fma_f32 v[180:181], v[54:55], v[54:55], v[180:181]
	v_pk_fma_f32 v[178:179], v[64:65], v[64:65], v[178:179]
	v_pk_fma_f32 v[180:181], v[48:49], v[48:49], v[180:181]
	v_pk_fma_f32 v[178:179], v[66:67], v[66:67], v[178:179]
	v_pk_fma_f32 v[180:181], v[50:51], v[50:51], v[180:181]
	v_pk_add_f32 v[178:179], v[178:179], v[180:181]
	v_add_f32_e32 v169, v178, v179
	v_mov_b32_e32 v177, v169
	v_pk_mul_f32 v[178:179], v[68:69], v[76:77]
	v_pk_mul_f32 v[180:181], v[70:71], v[78:79]
	v_pk_mul_f32 v[182:183], v[64:65], v[72:73]
	v_pk_mul_f32 v[184:185], v[66:67], v[74:75]
	v_pk_mul_f32 v[186:187], v[52:53], v[60:61]
	v_pk_mul_f32 v[188:189], v[54:55], v[62:63]
	v_pk_mul_f32 v[190:191], v[48:49], v[56:57]
	v_pk_mul_f32 v[192:193], v[50:51], v[58:59]
	v_permlane16_swap_b32_e32 v177, v169
	v_cvt_pk_bf16_f32 v178, v178, v179
	v_cvt_pk_bf16_f32 v179, v180, v181
	v_cvt_pk_bf16_f32 v180, v182, v183
	v_cvt_pk_bf16_f32 v181, v184, v185
	v_cvt_pk_bf16_f32 v182, v186, v187
	v_cvt_pk_bf16_f32 v183, v188, v189
	v_cvt_pk_bf16_f32 v184, v190, v191
	v_cvt_pk_bf16_f32 v185, v192, v193
	v_add_f32_e32 v169, v169, v177
	v_mov_b32_e32 v177, v169
	v_add_u32_e32 v167, 0x40000, v165
	global_store_dwordx4 v167, v[178:181], s[10:11]
	global_store_dwordx4 v167, v[182:185], s[10:11] offset:256
	v_permlane32_swap_b32_e32 v177, v169
	v_add_u32_e32 v152, 0x2000, v166
	s_nop 0
	v_add_f32_e32 v169, v169, v177
	s_and_saveexec_b64 s[34:35], s[4:5]
	global_store_dword v152, v169, s[12:13]
	s_mov_b64 exec, s[34:35]
	s_waitcnt vmcnt(29)
	v_pk_add_f32 v[44:45], v[44:45], v[194:195]
	v_pk_add_f32 v[46:47], v[46:47], v[196:197]
	v_pk_add_f32 v[40:41], v[40:41], v[198:199]
	v_pk_add_f32 v[42:43], v[42:43], v[200:201]
	v_pk_add_f32 v[36:37], v[36:37], v[202:203]
	v_pk_add_f32 v[38:39], v[38:39], v[204:205]
	v_pk_add_f32 v[32:33], v[32:33], v[206:207]
	v_pk_add_f32 v[34:35], v[34:35], v[208:209]
	v_add_u32_e32 v168, 0x90000, v164
	global_store_dwordx4 v168, v[44:47], s[84:85]
	global_store_dwordx4 v168, v[40:43], s[84:85] offset:16
	global_store_dwordx4 v168, v[36:39], s[84:85] offset:512
	global_store_dwordx4 v168, v[32:35], s[84:85] offset:528
	v_pk_mul_f32 v[194:195], v[44:45], v[44:45]
	v_pk_mul_f32 v[196:197], v[36:37], v[36:37]
	v_pk_fma_f32 v[194:195], v[46:47], v[46:47], v[194:195]
	v_pk_fma_f32 v[196:197], v[38:39], v[38:39], v[196:197]
	v_pk_fma_f32 v[194:195], v[40:41], v[40:41], v[194:195]
	v_pk_fma_f32 v[196:197], v[32:33], v[32:33], v[196:197]
	v_pk_fma_f32 v[194:195], v[42:43], v[42:43], v[194:195]
	v_pk_fma_f32 v[196:197], v[34:35], v[34:35], v[196:197]
	v_pk_add_f32 v[194:195], v[194:195], v[196:197]
	v_add_f32_e32 v169, v194, v195
	v_mov_b32_e32 v177, v169
	v_pk_mul_f32 v[194:195], v[44:45], v[76:77]
	v_pk_mul_f32 v[196:197], v[46:47], v[78:79]
	v_pk_mul_f32 v[198:199], v[40:41], v[72:73]
	v_pk_mul_f32 v[200:201], v[42:43], v[74:75]
	v_pk_mul_f32 v[202:203], v[36:37], v[60:61]
	v_pk_mul_f32 v[204:205], v[38:39], v[62:63]
	v_pk_mul_f32 v[206:207], v[32:33], v[56:57]
	v_pk_mul_f32 v[208:209], v[34:35], v[58:59]
	v_permlane16_swap_b32_e32 v177, v169
	v_cvt_pk_bf16_f32 v194, v194, v195
	v_cvt_pk_bf16_f32 v195, v196, v197
	v_cvt_pk_bf16_f32 v196, v198, v199
	v_cvt_pk_bf16_f32 v197, v200, v201
	v_cvt_pk_bf16_f32 v198, v202, v203
	v_cvt_pk_bf16_f32 v199, v204, v205
	v_cvt_pk_bf16_f32 v200, v206, v207
	v_cvt_pk_bf16_f32 v201, v208, v209
	v_add_f32_e32 v169, v169, v177
	v_mov_b32_e32 v177, v169
	v_add_u32_e32 v167, 0x48000, v165
	global_store_dwordx4 v167, v[194:197], s[10:11]
	global_store_dwordx4 v167, v[198:201], s[10:11] offset:256
	v_permlane32_swap_b32_e32 v177, v169
	v_add_u32_e32 v152, 0x2400, v166
	s_nop 0
	v_add_f32_e32 v169, v169, v177
	s_and_saveexec_b64 s[34:35], s[4:5]
	global_store_dword v152, v169, s[12:13]
	s_mov_b64 exec, s[34:35]
	s_waitcnt vmcnt(25)
; __device__ __forceinline__ u32x4 pack8(const f32x4 a, const f32x4 b) { u32x4 w; w.x = cvt_pk_bf16(a[0], a[1]); w.y = cvt_pk_bf16(a[2], a[3]); w.z = cvt_pk_bf16(b[0], b[1]); w.w = cvt_pk_bf16(b[2], b[3]); return w; }
; __device__ __forceinline__ float dot4(const f32x4 a, const f32x4 b) { return (a[0] * b[0] + a[1] * b[1]) + (a[2] * b[2] + a[3] * b[3]); }
;     __device__ __forceinline__ void operator()(const f32x4 (&acc)[2][2][4][2], const Unit& u, int wr, int wc, int fr, int fq) const {
;     ...
;             for (int m = 0; m < 4; ++m) { const int row = rbase + ai * 128 + m * 16; const float* xr = (row < MP ? xp + (size_t)row * 1024 : xs + (size_t)(row - MP) * 1024) + cb;
;                 float ss = 0.f;
; #pragma unroll
;                 for (int bj = 0; bj < 2; ++bj) { const f32x4 h0 = *(const f32x4*)(xr + bj * 128) + acc[ai][bj][m][0], h1 = *(const f32x4*)(xr + bj * 128 + 4) + acc[ai][bj][m][1];
;                     float* yp = y + (size_t)row * 1024 + cb + bj * 128; *(f32x4*)yp = h0; *(f32x4*)(yp + 4) = h1;
;                     ss += dot4(h0, h0) + dot4(h1, h1);
;                     *(u32x4*)(HN + (size_t)row * 1024 + cb + bj * 128) = pack8(h0 * w[bj][0], h1 * w[bj][1]); }
;                 ss += __shfl_xor(ss, 16); ss += __shfl_xor(ss, 32);
;                 if (fq == 0) SSP[(size_t)row * 16 + u.pn * 4 + wc] = ss;
;                 asm volatile("" ::: "memory"); }
	v_pk_add_f32 v[28:29], v[28:29], v[210:211]
	v_pk_add_f32 v[30:31], v[30:31], v[212:213]
	v_pk_add_f32 v[24:25], v[24:25], v[214:215]
	v_pk_add_f32 v[26:27], v[26:27], v[216:217]
	v_pk_add_f32 v[20:21], v[20:21], v[218:219]
	v_pk_add_f32 v[22:23], v[22:23], v[220:221]
	v_pk_add_f32 v[16:17], v[16:17], v[222:223]
	v_pk_add_f32 v[18:19], v[18:19], v[224:225]
	v_add_u32_e32 v168, 0xa0000, v164
	global_store_dwordx4 v168, v[28:31], s[84:85]
	global_store_dwordx4 v168, v[24:27], s[84:85] offset:16
	global_store_dwordx4 v168, v[20:23], s[84:85] offset:512
	global_store_dwordx4 v168, v[16:19], s[84:85] offset:528
	v_pk_mul_f32 v[210:211], v[28:29], v[28:29]
	v_pk_mul_f32 v[212:213], v[20:21], v[20:21]
	v_pk_fma_f32 v[210:211], v[30:31], v[30:31], v[210:211]
	v_pk_fma_f32 v[212:213], v[22:23], v[22:23], v[212:213]
	v_pk_fma_f32 v[210:211], v[24:25], v[24:25], v[210:211]
	v_pk_fma_f32 v[212:213], v[16:17], v[16:17], v[212:213]
	v_pk_fma_f32 v[210:211], v[26:27], v[26:27], v[210:211]
	v_pk_fma_f32 v[212:213], v[18:19], v[18:19], v[212:213]
	v_pk_add_f32 v[210:211], v[210:211], v[212:213]
	v_add_f32_e32 v169, v210, v211
	v_mov_b32_e32 v177, v169
	v_pk_mul_f32 v[210:211], v[28:29], v[76:77]
	v_pk_mul_f32 v[212:213], v[30:31], v[78:79]
	v_pk_mul_f32 v[214:215], v[24:25], v[72:73]
	v_pk_mul_f32 v[216:217], v[26:27], v[74:75]
	v_pk_mul_f32 v[218:219], v[20:21], v[60:61]
	v_pk_mul_f32 v[220:221], v[22:23], v[62:63]
	v_pk_mul_f32 v[222:223], v[16:17], v[56:57]
	v_pk_mul_f32 v[224:225], v[18:19], v[58:59]
	v_permlane16_swap_b32_e32 v177, v169
	v_cvt_pk_bf16_f32 v210, v210, v211
	v_cvt_pk_bf16_f32 v211, v212, v213
	v_cvt_pk_bf16_f32 v212, v214, v215
	v_cvt_pk_bf16_f32 v213, v216, v217
	v_cvt_pk_bf16_f32 v214, v218, v219
	v_cvt_pk_bf16_f32 v215, v220, v221
	v_cvt_pk_bf16_f32 v216, v222, v223
	v_cvt_pk_bf16_f32 v217, v224, v225
	v_add_f32_e32 v169, v169, v177
	v_mov_b32_e32 v177, v169
	v_add_u32_e32 v167, 0x50000, v165
	global_store_dwordx4 v167, v[210:213], s[10:11]
	global_store_dwordx4 v167, v[214:217], s[10:11] offset:256
	v_permlane32_swap_b32_e32 v177, v169
	v_add_u32_e32 v152, 0x2800, v166
	s_nop 0
	v_add_f32_e32 v169, v169, v177
	s_and_saveexec_b64 s[34:35], s[4:5]
	global_store_dword v152, v169, s[12:13]
	s_mov_b64 exec, s[34:35]
	s_waitcnt vmcnt(21)
	v_pk_add_f32 v[12:13], v[12:13], v[228:229]
	v_pk_add_f32 v[14:15], v[14:15], v[230:231]
	v_pk_add_f32 v[8:9], v[8:9], v[232:233]
	v_pk_add_f32 v[10:11], v[10:11], v[234:235]
	v_pk_add_f32 v[4:5], v[4:5], v[236:237]
	v_pk_add_f32 v[6:7], v[6:7], v[238:239]
	v_pk_add_f32 v[0:1], v[0:1], v[240:241]
	v_pk_add_f32 v[2:3], v[2:3], v[242:243]
	v_add_u32_e32 v168, 0xb0000, v164
	global_store_dwordx4 v168, v[12:15], s[84:85]
	global_store_dwordx4 v168, v[8:11], s[84:85] offset:16
	global_store_dwordx4 v168, v[4:7], s[84:85] offset:512
	global_store_dwordx4 v168, v[0:3], s[84:85] offset:528
	v_pk_mul_f32 v[228:229], v[12:13], v[12:13]
	v_pk_mul_f32 v[230:231], v[4:5], v[4:5]
	v_pk_fma_f32 v[228:229], v[14:15], v[14:15], v[228:229]
	v_pk_fma_f32 v[230:231], v[6:7], v[6:7], v[230:231]
	v_pk_fma_f32 v[228:229], v[8:9], v[8:9], v[228:229]
	v_pk_fma_f32 v[230:231], v[0:1], v[0:1], v[230:231]
	v_pk_fma_f32 v[228:229], v[10:11], v[10:11], v[228:229]
	v_pk_fma_f32 v[230:231], v[2:3], v[2:3], v[230:231]
	v_pk_add_f32 v[228:229], v[228:229], v[230:231]
	v_add_f32_e32 v169, v228, v229
	v_mov_b32_e32 v177, v169
	v_pk_mul_f32 v[228:229], v[12:13], v[76:77]
	v_pk_mul_f32 v[230:231], v[14:15], v[78:79]
	v_pk_mul_f32 v[232:233], v[8:9], v[72:73]
	v_pk_mul_f32 v[234:235], v[10:11], v[74:75]
	v_pk_mul_f32 v[236:237], v[4:5], v[60:61]
	v_pk_mul_f32 v[238:239], v[6:7], v[62:63]
	v_pk_mul_f32 v[240:241], v[0:1], v[56:57]
	v_pk_mul_f32 v[242:243], v[2:3], v[58:59]
	v_permlane16_swap_b32_e32 v177, v169
	v_cvt_pk_bf16_f32 v228, v228, v229
	v_cvt_pk_bf16_f32 v229, v230, v231
	v_cvt_pk_bf16_f32 v230, v232, v233
	v_cvt_pk_bf16_f32 v231, v234, v235
	v_cvt_pk_bf16_f32 v232, v236, v237
	v_cvt_pk_bf16_f32 v233, v238, v239
	v_cvt_pk_bf16_f32 v234, v240, v241
	v_cvt_pk_bf16_f32 v235, v242, v243
	v_add_f32_e32 v169, v169, v177
	v_mov_b32_e32 v177, v169
	v_add_u32_e32 v167, 0x58000, v165
	global_store_dwordx4 v167, v[228:231], s[10:11]
	global_store_dwordx4 v167, v[232:235], s[10:11] offset:256
	v_permlane32_swap_b32_e32 v177, v169
	v_add_u32_e32 v152, 0x2c00, v166
	s_nop 0
	v_add_f32_e32 v169, v169, v177
	s_and_saveexec_b64 s[34:35], s[4:5]
	global_store_dword v152, v169, s[12:13]
	s_mov_b64 exec, s[34:35]
	s_andn2_b64 vcc, exec, s[6:7]
	s_mov_b64 s[6:7], -1
	s_cbranch_vccnz .LBB0_1419
	s_andn2_b64 vcc, exec, s[16:17]
	s_cbranch_vccnz .LBB0_1418
	s_barrier
	s_branch .LBB0_1418
